# scan stage X: static priority raise around the state-dependent MFMA block (waves 4-7)
# baseline (speedup 1.0000x reference)
.Lsx0_c:
	s_or_b64 exec, exec, s[2:3]
	v_mov_b32_e32 v22, 0
	v_mov_b32_e32 v23, 0
	v_mov_b32_e32 v24, 0
	v_mov_b32_e32 v25, 0
	s_and_saveexec_b64 s[2:3], s[56:57]
	s_cbranch_execz .LBB0_403
	s_setprio 2
	ds_read_b128 v[48:51], v174
	ds_read_b128 v[60:63], v192 offset:49152
	ds_read_b128 v[52:55], v174 offset:64
	ds_read_b128 v[64:67], v192 offset:49216
	ds_read_b128 v[56:59], v175
	ds_read_b128 v[68:71], v199
	ds_read_b128 v[72:75], v192 offset:58368
	ds_read_b128 v[76:79], v192 offset:58432
	s_waitcnt lgkmcnt(6)
	v_mfma_f32_16x16x32_bf16 v[30:33], v[48:51], v[60:63], 0
	s_waitcnt lgkmcnt(4)
	v_mfma_f32_16x16x32_bf16 v[30:33], v[52:55], v[64:67], v[30:33]
	s_waitcnt lgkmcnt(2)
	v_mfma_f32_16x16x32_bf16 v[30:33], v[56:59], v[68:71], v[30:33]
	s_waitcnt lgkmcnt(1)
	v_mfma_f32_16x16x32_bf16 v[22:25], v[48:51], v[72:75], 0
	s_waitcnt lgkmcnt(0)
	v_mfma_f32_16x16x32_bf16 v[22:25], v[52:55], v[76:79], v[22:25]
	s_cmp_lg_u32 s21, 0
	s_cbranch_scc0 .Lsx0_d
	v_cvt_pk_bf16_f32 v240, v236, v237
	global_store_dword v[238:239], v240, off
.Lsx0_d:
	s_nop 3
	ds_write_b128 v176, v[30:33]
	s_setprio 0

.Lsx1_c:
	s_or_b64 exec, exec, s[74:75]
	v_mov_b32_e32 v22, 0
	v_mov_b32_e32 v23, 0
	v_mov_b32_e32 v24, 0
	v_mov_b32_e32 v25, 0
	s_and_saveexec_b64 s[74:75], s[56:57]
	s_cbranch_execz .LBB0_432
	s_setprio 2
	ds_read_b128 v[48:51], v174
	ds_read_b128 v[60:63], v192 offset:51456
	ds_read_b128 v[52:55], v174 offset:64
	ds_read_b128 v[64:67], v192 offset:51520
	ds_read_b128 v[56:59], v175 offset:5120
	ds_read_b128 v[68:71], v199
	ds_read_b128 v[72:75], v192 offset:60672
	ds_read_b128 v[76:79], v192 offset:60736
	s_waitcnt lgkmcnt(6)
	v_mfma_f32_16x16x32_bf16 v[30:33], v[48:51], v[60:63], 0
	s_waitcnt lgkmcnt(4)
	v_mfma_f32_16x16x32_bf16 v[30:33], v[52:55], v[64:67], v[30:33]
	s_waitcnt lgkmcnt(2)
	v_mfma_f32_16x16x32_bf16 v[30:33], v[56:59], v[68:71], v[30:33]
	s_waitcnt lgkmcnt(1)
	v_mfma_f32_16x16x32_bf16 v[22:25], v[48:51], v[72:75], 0
	s_waitcnt lgkmcnt(0)
	v_mfma_f32_16x16x32_bf16 v[22:25], v[52:55], v[76:79], v[22:25]
	v_cvt_pk_bf16_f32 v240, v236, v237
	global_store_dword v[238:239], v240, off
	s_nop 3
	ds_write_b128 v176, v[30:33]
	s_setprio 0
